# phase-0 weight transposition rewritten: 9 tiles in flight per workgroup, next batch loaded before current stores
# baseline (speedup 1.0000x reference)
; __device__ void run_phase(const Params& p, unsigned char* lds, int ph) {
;     ...
;             else if (it < 2096) { const int j = it - 48, n = j >> 4, bh = j & 15, h = bh & 3;
;                 prep_unit(lds, bh, n, (const bf16_t*)(ws + WS_PC), (const float*)(ws + WS_SCAL), p.in[I_CONVW] + (size_t)l * 4 * 1536, p.in[I_ALOG][l * 4 + h], p.in[I_DTB][l * 4 + h],
;                           ws + WS_PREP + (size_t)(bh * 128 + n) * PREP_UNIT, (float*)(ws + WS_EGL), uflag + bh * 128 + n, fval); }
.LBB0_449:
	s_or_b64 exec, exec, s[12:13]
	s_branch .Lrp_0
	s_nop 0
	s_nop 0
	s_nop 0
	s_nop 0
	s_nop 0
	s_nop 0
	s_nop 0
	s_nop 0
	s_nop 0
	s_nop 0
	s_nop 0
	s_nop 0
	s_nop 0
	s_nop 0
	s_nop 0
	s_nop 0
	s_nop 0
	s_nop 0
	s_nop 0
	s_nop 0
	s_nop 0
	s_nop 0
	s_nop 0
	s_nop 0
	s_nop 0
	s_nop 0
	s_nop 0
	s_nop 0
	s_nop 0
	s_nop 0
	s_nop 0
	s_nop 0
	s_nop 0
	s_nop 0
	s_nop 0
	s_nop 0
	s_nop 0
	s_nop 0
	s_nop 0
	s_nop 0
	s_nop 0
	s_nop 0
	s_nop 0
	s_nop 0
	s_nop 0
	s_nop 0
	s_nop 0
	s_nop 0
	s_nop 0
	s_nop 0
	s_nop 0
	s_nop 0
	s_nop 0
	s_nop 0
	s_nop 0
	s_nop 0
	s_nop 0
	s_nop 0
	s_nop 0
	s_nop 0
	s_nop 0
	s_nop 0
	s_nop 0
	s_nop 0
	s_nop 0
	s_nop 0
	s_nop 0
	s_nop 0
	s_nop 0
	s_nop 0
	s_nop 0
	s_nop 0
	s_nop 0
	s_nop 0
	s_nop 0
	s_nop 0
	s_nop 0
	s_nop 0
	s_nop 0
	s_nop 0
	s_nop 0
	s_nop 0
	s_nop 0
	s_nop 0
	s_nop 0
	s_nop 0
	s_nop 0
	s_nop 0
	s_nop 0
	s_nop 0
	s_nop 0
	s_nop 0
	s_nop 0
	s_nop 0
	s_nop 0
	s_nop 0
	s_nop 0
	s_nop 0
	s_nop 0
	s_nop 0
	s_nop 0
	s_nop 0
	s_nop 0
	s_nop 0
	s_nop 0
	s_nop 0
	s_nop 0
	s_nop 0
	s_nop 0
	s_nop 0
	s_nop 0
	s_nop 0
	s_nop 0
	s_nop 0
	s_nop 0
	s_nop 0
	s_nop 0
	s_nop 0
	s_nop 0
	s_nop 0
	s_nop 0
	s_nop 0
	s_nop 0
	s_nop 0
	s_nop 0
	s_nop 0
	s_nop 0
	s_nop 0
	s_nop 0
	s_nop 0
	s_nop 0
	s_nop 0
	s_nop 0
	s_nop 0
	s_nop 0
	s_nop 0
	s_nop 0
	s_nop 0
	s_nop 0
	s_nop 0
	s_nop 0
	s_nop 0
	s_nop 0
	s_nop 0
	s_nop 0
	s_nop 0
	s_nop 0
	s_nop 0
	s_nop 0
	s_nop 0
	s_nop 0
	s_nop 0
	s_nop 0
	s_nop 0
	s_nop 0
	s_nop 0
	s_nop 0
	s_nop 0
	s_nop 0
	s_nop 0
	s_nop 0
	s_nop 0
	s_nop 0
	s_nop 0
	s_nop 0
	s_nop 0
	s_nop 0
	s_nop 0
	s_nop 0
	s_nop 0
	s_nop 0
	s_nop 0
	s_nop 0
	s_nop 0
	s_nop 0
	s_nop 0
	s_nop 0
	s_nop 0
	s_nop 0
	s_nop 0
	s_nop 0
	s_nop 0
	s_nop 0
	s_nop 0
	s_nop 0
	s_nop 0
	s_nop 0
	s_nop 0
	s_nop 0
	s_nop 0
	s_nop 0
	s_nop 0
	s_nop 0
	s_nop 0
	s_nop 0
	s_nop 0
	s_nop 0
	s_nop 0
	s_nop 0
	s_nop 0
	s_nop 0
	s_nop 0
	s_nop 0
	s_nop 0
	s_nop 0
	s_nop 0
	s_nop 0
	s_nop 0
	s_nop 0
	s_nop 0
	s_nop 0
	s_nop 0
	s_nop 0
	s_nop 0
	s_nop 0
	s_nop 0
	s_nop 0
	s_nop 0
	s_nop 0
	s_nop 0
	s_nop 0
	s_nop 0
	s_nop 0
	s_nop 0
	s_nop 0
	s_nop 0
	s_nop 0
	s_nop 0
	s_nop 0
	s_nop 0
	s_nop 0
	s_nop 0
	s_nop 0
	s_nop 0
	s_nop 0
	s_nop 0
	s_nop 0
	s_nop 0
	s_nop 0
	s_nop 0
	s_nop 0
	s_nop 0
	s_nop 0
	s_nop 0
	s_nop 0
	s_nop 0
	s_nop 0
	s_nop 0
	s_nop 0
	s_nop 0
	s_nop 0
	s_nop 0
	s_nop 0
	s_nop 0
	s_nop 0
	s_nop 0
	s_nop 0
	s_nop 0
	s_nop 0
	s_nop 0
	s_nop 0
	s_nop 0
	s_nop 0
	s_nop 0
	s_nop 0
	s_nop 0
	s_nop 0
	s_nop 0
	s_nop 0
	s_nop 0
	s_nop 0
	s_nop 0
	s_nop 0
	s_nop 0
	s_nop 0
	s_nop 0
	s_nop 0
	s_nop 0
	s_nop 0
	s_nop 0
	s_nop 0
	s_nop 0
	s_nop 0
	s_nop 0
	s_nop 0
	s_nop 0
	s_nop 0
	s_nop 0
	s_nop 0
	s_nop 0
	s_nop 0
	s_nop 0
	s_nop 0
	s_nop 0
	s_nop 0
	s_nop 0
	s_nop 0
	s_nop 0
	s_nop 0
	s_nop 0
	s_nop 0
	s_nop 0
	s_nop 0
	s_nop 0
	s_nop 0
	s_nop 0
	s_nop 0
	s_nop 0
	s_nop 0
	s_nop 0
	s_nop 0
	s_nop 0
	s_nop 0
	s_nop 0
	s_nop 0
	s_nop 0
	s_nop 0
	s_nop 0
	s_nop 0
	s_nop 0
	s_nop 0
	s_nop 0
	s_nop 0
	s_nop 0
	s_nop 0
	s_nop 0
	s_nop 0
	s_nop 0
	s_nop 0
	s_nop 0
	s_nop 0
	s_nop 0
	s_nop 0
	s_nop 0
	s_nop 0
	s_nop 0
	s_nop 0
	s_nop 0
	s_nop 0
	s_nop 0
	s_nop 0
	s_nop 0
	s_nop 0
	s_nop 0
	s_nop 0
	s_nop 0
	s_nop 0
	s_nop 0
	s_nop 0
	s_nop 0
	s_nop 0
	s_nop 0
	s_nop 0
	s_nop 0
	s_nop 0
	s_nop 0
	s_nop 0
	s_nop 0
	s_nop 0
	s_nop 0
	s_nop 0
	s_nop 0
	s_nop 0
	s_nop 0
	s_nop 0
	s_nop 0
	s_nop 0
	s_nop 0
	s_nop 0
	s_nop 0
	s_nop 0
	s_nop 0
	s_nop 0
	s_nop 0
	s_nop 0
	s_nop 0
	s_nop 0
	s_nop 0
	s_nop 0
	s_nop 0
	s_nop 0
	s_nop 0
	s_nop 0
	s_nop 0
	s_nop 0
	s_nop 0
	s_nop 0
	s_nop 0
	s_nop 0
	s_nop 0
	s_nop 0
	s_nop 0
	s_nop 0
	s_nop 0
	s_nop 0
	s_nop 0
	s_nop 0
	s_nop 0
	s_nop 0
	s_nop 0
	s_nop 0
	s_nop 0
	s_nop 0
	s_nop 0
	s_nop 0
	s_nop 0
	s_nop 0
	s_nop 0
	s_nop 0
	s_nop 0
	s_nop 0
	s_nop 0
	s_nop 0
	s_nop 0
	s_nop 0
	s_nop 0
	s_nop 0
	s_nop 0
	s_nop 0
	s_nop 0
	s_nop 0
	s_nop 0
	s_nop 0
	s_nop 0
	s_nop 0
	s_nop 0
	s_nop 0
	s_nop 0
	s_nop 0
	s_nop 0
	s_nop 0
; __device__ void run_phase(const Params& p, unsigned char* lds, int ph) {
;     ...
;             else if (it < 2096) { const int j = it - 48, n = j >> 4, bh = j & 15, h = bh & 3;
;                 prep_unit(lds, bh, n, (const bf16_t*)(ws + WS_PC), (const float*)(ws + WS_SCAL), p.in[I_CONVW] + (size_t)l * 4 * 1536, p.in[I_ALOG][l * 4 + h], p.in[I_DTB][l * 4 + h],
;                           ws + WS_PREP + (size_t)(bh * 128 + n) * PREP_UNIT, (float*)(ws + WS_EGL), uflag + bh * 128 + n, fval); }
	s_nop 0
	s_nop 0
	s_nop 0
	s_nop 0
	s_nop 0
	s_nop 0
	s_nop 0
	s_nop 0
	s_nop 0
	s_nop 0
	s_nop 0
	s_nop 0
	s_nop 0
	s_nop 0
	s_nop 0
	s_nop 0
	s_nop 0
	s_nop 0
	s_nop 0
	s_nop 0
	s_nop 0
	s_nop 0
	s_nop 0
	s_nop 0
	s_nop 0
	s_nop 0
	s_nop 0
	s_nop 0
	s_nop 0
	s_nop 0
	s_nop 0
	s_nop 0
	s_nop 0
	s_nop 0
	s_nop 0
	s_nop 0
	s_nop 0
	s_nop 0
	s_nop 0
	s_nop 0
	s_nop 0
	s_nop 0
	s_nop 0
	s_nop 0
	s_nop 0
	s_nop 0
	s_nop 0
	s_nop 0
	s_nop 0
	s_nop 0
	s_nop 0
	s_nop 0
	s_nop 0
	s_nop 0
	s_nop 0
	s_nop 0
	s_nop 0
	s_nop 0
	s_nop 0
	s_nop 0
	s_nop 0
	s_nop 0
	s_nop 0
	s_nop 0
	s_nop 0
	s_nop 0
	s_nop 0
	s_nop 0
	s_nop 0
	s_nop 0
	s_nop 0
	s_nop 0
	s_nop 0
	s_nop 0
	s_nop 0
	s_nop 0
	s_nop 0
	s_nop 0
	s_nop 0
	s_nop 0
	s_nop 0
	s_nop 0
	s_nop 0
	s_nop 0
	s_nop 0
	s_nop 0
	s_nop 0
	s_nop 0
	s_nop 0
	s_nop 0
	s_nop 0
	s_nop 0
	s_nop 0
	s_nop 0
	s_nop 0
	s_nop 0
	s_nop 0
	s_nop 0
	s_nop 0
	s_nop 0
	s_nop 0
	s_nop 0
	s_nop 0
	s_nop 0
	s_nop 0
	s_nop 0
	s_nop 0
	s_nop 0
	s_nop 0
	s_nop 0
	s_nop 0
	s_nop 0
	s_nop 0
	s_nop 0
	s_nop 0
	s_nop 0
	s_nop 0
	s_nop 0
	s_nop 0
	s_nop 0
	s_nop 0
	s_nop 0
	s_nop 0
	s_nop 0
	s_nop 0
	s_nop 0
	s_nop 0
	s_nop 0
	s_nop 0
	s_nop 0
	s_nop 0
	s_nop 0
	s_nop 0
	s_nop 0
	s_nop 0
	s_nop 0
	s_nop 0
	s_nop 0
	s_nop 0
	s_nop 0
	s_nop 0
	s_nop 0
	s_nop 0
	s_nop 0
	s_nop 0
	s_nop 0
	s_nop 0
	s_nop 0
	s_nop 0
	s_nop 0
	s_nop 0
	s_nop 0
	s_nop 0
	s_nop 0
	s_nop 0
	s_nop 0
	s_nop 0
	s_nop 0
	s_nop 0
	s_nop 0
	s_nop 0
	s_nop 0
	s_nop 0
	s_nop 0
	s_nop 0
	s_nop 0
	s_nop 0
	s_nop 0
	s_nop 0
	s_nop 0
	s_nop 0
	s_nop 0
	s_nop 0
	s_nop 0
	s_nop 0
	s_nop 0
	s_nop 0
	s_nop 0
	s_nop 0
	s_nop 0
	s_nop 0
	s_nop 0
	s_nop 0
	s_nop 0
	s_nop 0
	s_nop 0
	s_nop 0
	s_nop 0
	s_nop 0
	s_nop 0
	s_nop 0
	s_nop 0
	s_nop 0
	s_nop 0
	s_nop 0
	s_nop 0
	s_nop 0
	s_nop 0
	s_nop 0
	s_nop 0
	s_nop 0
	s_nop 0
	s_nop 0
	s_nop 0
	s_nop 0
	s_nop 0
	s_nop 0
	s_nop 0
	s_nop 0
	s_nop 0
	s_nop 0
	s_nop 0
	s_nop 0
	s_nop 0
	s_nop 0
	s_nop 0
	s_nop 0
	s_nop 0
	s_nop 0
	s_nop 0
	s_nop 0
	s_nop 0
	s_nop 0
	s_nop 0
	s_nop 0
	s_nop 0
	s_nop 0
	s_nop 0
	s_nop 0
	s_nop 0
	s_nop 0
	s_nop 0
	s_nop 0
	s_nop 0
	s_nop 0
	s_nop 0
	s_nop 0
	s_nop 0
	s_nop 0
	s_nop 0
	s_nop 0
	s_nop 0
	s_nop 0
	s_nop 0
	s_nop 0
	s_nop 0
	s_nop 0
	s_nop 0
	s_nop 0
	s_nop 0
	s_nop 0
	s_nop 0
	s_nop 0
	s_nop 0
	s_nop 0
	s_nop 0
	s_nop 0
	s_nop 0
	s_nop 0
	s_nop 0
	s_nop 0
	s_nop 0
	s_nop 0
	s_nop 0
	s_nop 0
	s_nop 0
	s_nop 0
	s_nop 0
	s_nop 0
	s_nop 0
	s_nop 0
	s_nop 0
	s_nop 0
	s_nop 0
	s_nop 0
	s_nop 0
	s_nop 0
	s_nop 0
	s_nop 0
	s_nop 0
	s_nop 0
	s_nop 0
	s_nop 0
	s_nop 0
	s_nop 0
	s_nop 0
	s_nop 0
	s_nop 0
	s_nop 0
	s_nop 0
	s_nop 0
	s_nop 0
	s_nop 0
	s_nop 0
	s_nop 0
	s_nop 0
	s_nop 0
	s_nop 0
	s_nop 0
	s_nop 0
	s_nop 0
	s_nop 0
	s_nop 0
	s_nop 0
	s_nop 0
	s_nop 0
	s_nop 0
	s_nop 0
	s_nop 0
	s_nop 0
	s_nop 0
	s_nop 0
	s_nop 0
	s_nop 0
	s_nop 0
	s_nop 0
	s_nop 0
	s_nop 0
	s_nop 0
	s_nop 0
	s_nop 0
	s_nop 0
	s_nop 0
	s_nop 0
	s_nop 0
	s_nop 0
	s_nop 0
	s_nop 0
	s_nop 0
	s_nop 0
	s_nop 0
	s_nop 0
	s_nop 0
	s_nop 0
	s_nop 0
	s_nop 0
	s_nop 0
	s_nop 0
	s_nop 0
	s_nop 0
	s_nop 0
	s_nop 0
	s_nop 0
	s_nop 0
	s_nop 0
	s_nop 0
	s_nop 0
	s_nop 0
	s_nop 0
	s_nop 0
	s_nop 0
	s_nop 0
	s_nop 0
	s_nop 0
	s_nop 0
	s_nop 0
	s_nop 0
	s_nop 0
	s_nop 0
	s_nop 0
	s_nop 0
	s_nop 0
	s_nop 0
	s_nop 0
	s_nop 0
	s_nop 0
	s_nop 0
	s_nop 0
	s_nop 0
	s_nop 0
	s_nop 0
	s_nop 0
	s_nop 0
	s_nop 0
	s_nop 0
	s_nop 0
	s_nop 0
	s_nop 0
	s_nop 0
	s_nop 0
	s_nop 0
	s_nop 0
	s_nop 0
	s_nop 0
	s_nop 0
	s_nop 0
	s_nop 0
	s_nop 0
	s_nop 0
	s_nop 0
	s_nop 0
	s_nop 0
	s_nop 0
	s_nop 0
	s_nop 0
	s_nop 0
	s_nop 0
	s_nop 0
	s_nop 0
	s_nop 0
	s_nop 0
	s_nop 0
	s_nop 0
	s_nop 0
	s_nop 0
	s_nop 0
	s_nop 0
	s_nop 0
	s_nop 0
	s_nop 0
	s_nop 0
	s_nop 0
	s_nop 0
	s_nop 0
	s_nop 0
	s_nop 0
	s_nop 0
	s_nop 0
	s_nop 0
	s_nop 0
	s_nop 0
	s_nop 0
	s_nop 0
	s_nop 0
	s_nop 0
	s_nop 0
	s_nop 0
	s_nop 0
	s_nop 0
	s_nop 0
	s_nop 0
	s_nop 0
	s_nop 0
	s_nop 0
	s_nop 0
	s_nop 0
	s_nop 0
	s_nop 0

; __device__ __forceinline__ int my_bid() { int t = (int)blockIdx.x; asm volatile("" : "+s"(t)); return t; }
; __device__ __forceinline__ int my_gdim() { int t = (int)gridDim.x; asm volatile("" : "+s"(t)); return t; }
; __device__ void phase_prologue(const Params& p, unsigned char* lds) {
;     ...
;         auto tdesc = [&](int it) -> TD {
;             const int l = it / T_L; int r = it % T_L;
;             if (r < T_IN) { const int kt = r / 56, nt = r % 56, d0 = nt * 64; const int s0 = d0 < 1536 ? d0 : (d0 < 3072 ? d0 + 4 : d0 + 12);
;                 return TD{p.in[I_WIN] + (size_t)l * DM * DIN + (size_t)(kt * 64) * DIN + s0, (bf16_t*)(p.ws + WS_WTIN) + (size_t)l * NPROJ * DM + (size_t)d0 * DM + kt * 64, DIN, DM}; }
;             if ((r -= T_IN) < T_OUT) { const int kt = r / 16, nt = r % 16;
;                 return TD{p.in[I_WOUT] + (size_t)l * DM * DM + (size_t)(kt * 64) * DM + nt * 64, (bf16_t*)(p.ws + WS_WTOUT) + (size_t)l * DM * DM + (size_t)(nt * 64) * DM + kt * 64, DM, DM}; }
;             if ((r -= T_OUT) < T_UP) { const int kt = r / 88, nt = r % 88; const int d0 = nt * 64, pn = d0 >> 8, w = d0 & 255, s0 = w < 128 ? pn * 128 + w : DFF + pn * 128 + (w - 128);
;                 return TD{p.in[I_WUP] + (size_t)l * DM * NUP + (size_t)(kt * 64) * NUP + s0, (bf16_t*)(p.ws + WS_WTUP) + (size_t)l * NUP * DM + (size_t)d0 * DM + kt * 64, NUP, DM}; }
;             r -= T_UP; const int kt = r / 16, nt = r % 16;
;             return TD{p.in[I_WDN] + (size_t)l * DFF * DM + (size_t)(kt * 64) * DM + nt * 64, (bf16_t*)(p.ws + WS_WTDN) + (size_t)l * DM * DFF + (size_t)(nt * 64) * DFF + kt * 64, DM, DFF};
;         };
;         const int kk0 = tid >> 4, n4 = (tid & 15) * 4;
;         const int nn = tid >> 3, k8 = (tid & 7) * 8;
;         int it = my_bid(); TD d{nullptr, nullptr, 0, 0}; f32x4 v0 = (f32x4){0.f, 0.f, 0.f, 0.f}, v1 = v0;
;         if (it < N_T) { d = tdesc(it); v0 = *(const f32x4*)(d.src + (size_t)kk0 * d.ldsrc + n4); v1 = *(const f32x4*)(d.src + (size_t)(kk0 + 32) * d.ldsrc + n4); }
;         while (it < N_T) {
;             const int itn = it + my_gdim(); TD dn{nullptr, nullptr, 0, 0}; f32x4 w0 = (f32x4){0.f, 0.f, 0.f, 0.f}, w1 = w0;
;             if (itn < N_T) { dn = tdesc(itn); w0 = *(const f32x4*)(dn.src + (size_t)kk0 * dn.ldsrc + n4); w1 = *(const f32x4*)(dn.src + (size_t)(kk0 + 32) * dn.ldsrc + n4); }
.LBB0_706:
	s_or_b64 exec, exec, s[0:1]
	v_lshlrev_b32_e32 v0, 2, v18
	v_readlane_b32 s18, v254, 0
	v_ashrrev_i32_e32 v20, 4, v18
	s_cmpk_gt_i32 s18, 0x197f
	v_and_b32_e32 v22, 60, v0
	s_cbranch_scc1 .LBB0_735
	s_add_u32 s19, s86, 0x2b00000
	s_addc_u32 s20, s87, 0
	s_add_u32 s21, s86, 0x1500000
	s_addc_u32 s22, s87, 0
	s_add_u32 s23, s86, 0x1100000
	s_addc_u32 s24, s87, 0
	s_add_u32 s25, s86, 0x300000
	s_addc_u32 s26, s87, 0
	s_load_dword s29, s[80:81], 0x0
	v_and_b32_e32 v2, 7, v18
	v_lshrrev_b32_e32 v112, 3, v18
	v_lshlrev_b32_e32 v113, 4, v2
	v_mul_u32_u24_e32 v110, 0x104, v20
	v_lshl_add_u32 v110, v22, 2, v110
	v_mul_u32_u24_e32 v111, 0x820, v2
	v_lshl_add_u32 v111, v112, 2, v111
	s_waitcnt lgkmcnt(0)
	s_mov_b32 s31, s18
	s_mul_i32 s35, s29, 9
	s_mov_b32 s28, s31
	s_mov_b32 s30, 0
.Lp0_para:
	s_min_i32 s18, s28, 0x197f
	s_mul_hi_i32 s6, s18, 0xa0a0a0a1
	s_add_i32 s6, s6, s18
	s_lshr_b32 s7, s6, 31
	s_ashr_i32 s6, s6, 11
	s_add_i32 s6, s6, s7
	s_mul_i32 s7, s6, 0xcc0
	s_sub_i32 s27, s18, s7
	s_cmpk_gt_i32 s27, 0x37f
	s_cbranch_scc0 .Lp0_ina
	s_cmpk_gt_u32 s27, 0x47f
	s_cbranch_scc0 .Lp0_outa
	s_cmpk_gt_u32 s27, 0x9ff
	s_cbranch_scc0 .Lp0_upa
	s_mul_i32 s8, s6, 0xb00000
	s_mul_hi_i32 s7, s6, 0xb00000
	s_add_u32 s10, s62, s8
	s_addc_u32 s7, s63, s7
	s_lshl_b32 s8, s27, 2
	s_and_b32 s8, s8, 0x7fffffc0
	s_add_i32 s84, s8, 0xffffd800
	s_lshl_b64 s[8:9], s[84:85], 12
	s_add_u32 s8, s10, s8
	s_addc_u32 s7, s7, s9
	s_lshl_b32 s9, s27, 6
	s_and_b32 s9, s9, 0x3c0
	s_lshl_b32 s10, s9, 2
	s_add_u32 s10, s8, s10
	s_addc_u32 s11, s7, 0
	s_mul_i32 s8, s6, 0x580000
	s_mul_hi_i32 s7, s6, 0x580000
	s_add_u32 s8, s19, s8
	s_addc_u32 s7, s20, s7
	s_mulk_i32 s9, 0x1600
	s_add_u32 s12, s8, s9
	s_addc_u32 s7, s7, 0
	s_lshl_b64 s[8:9], s[84:85], 1
	s_add_u32 s8, s12, s8
	s_movk_i32 s84, 0x77
	s_addc_u32 s9, s7, s9
	s_mov_b64 s[14:15], 0x400
	s_mov_b64 s[12:13], 0xb00
	s_branch .Lp0_havea
.Lp0_upa:
	s_add_i32 s7, s27, 0xfb80
	s_and_b32 s8, s7, 0xffff
	s_mul_i32 s8, s8, 0xba2f
	s_lshr_b32 s9, s8, 16
	s_lshr_b32 s8, s8, 22
	s_mulk_i32 s8, 0x58
	s_sub_i32 s7, s7, s8
	s_and_b32 s8, s7, 0xffff
	s_lshl_b32 s10, s8, 6
	s_lshl_b32 s8, s8, 5
	s_and_b32 s10, s10, 0xc0
	s_and_b32 s8, s8, 0xf80
	s_or_b32 s11, s8, s10
	s_add_i32 s8, s10, s8
	s_addk_i32 s8, 0xa80
	s_cmpk_lt_u32 s10, 0x80
	s_cselect_b32 s8, s11, s8
	s_mul_i32 s11, s6, 0x1600000
	s_mul_hi_i32 s10, s6, 0x1600000
	s_add_u32 s11, s60, s11
	s_addc_u32 s10, s61, s10
	s_and_b32 s9, s9, 0xffc0
	s_mul_i32 s12, s9, 0x5800
	s_add_u32 s11, s11, s12
	s_addc_u32 s12, s10, 0
	s_lshl_b32 s8, s8, 2
	s_add_u32 s10, s11, s8
	s_addc_u32 s11, s12, 0
	s_mul_i32 s12, s6, 0xb00000
	s_mul_hi_i32 s8, s6, 0xb00000
	s_add_u32 s12, s21, s12
	s_addc_u32 s8, s22, s8
	s_lshl_b32 s7, s7, 17
	s_add_u32 s7, s12, s7
	s_addc_u32 s12, s8, 0
	s_lshl_b32 s8, s9, 1
	s_add_u32 s8, s7, s8
	s_addc_u32 s9, s12, 0
	s_mov_b64 s[14:15], 0x1600
	s_mov_b64 s[12:13], 0x400
	s_branch .Lp0_havea
.Lp0_outa:
	s_ashr_i32 s7, s6, 31
	s_lshl_b64 s[8:9], s[6:7], 22
	s_add_u32 s10, s68, s8
	s_addc_u32 s11, s69, s9
	s_lshl_b32 s8, s27, 2
	s_and_b32 s8, s8, 0x1fc0
	s_add_i32 s84, s8, 0xfffff200
	s_lshl_b64 s[8:9], s[84:85], 12
	s_add_u32 s8, s10, s8
	s_addc_u32 s9, s11, s9
	s_lshl_b32 s10, s27, 6
	s_and_b32 s12, s10, 0x3c0
	s_lshl_b32 s10, s12, 2
	s_add_u32 s10, s8, s10
	s_addc_u32 s11, s9, 0
	s_lshl_b64 s[8:9], s[6:7], 21
	s_add_u32 s7, s23, s8
	s_addc_u32 s8, s24, s9
	s_lshl_b32 s9, s12, 11
	s_add_u32 s7, s7, s9
	s_addc_u32 s12, s8, 0
	s_lshl_b64 s[8:9], s[84:85], 1
	s_add_u32 s8, s7, s8
	s_movk_i32 s84, 0x77
	s_addc_u32 s9, s12, s9
	s_mov_b64 s[12:13], 0x400
	s_mov_b64 s[14:15], 0x400
	s_branch .Lp0_havea
.Lp0_ina:
	s_mul_i32 s7, s27, 0x4925
	s_lshr_b32 s8, s7, 31
	s_ashr_i32 s7, s7, 20
	s_add_i32 s7, s7, s8
	s_mul_i32 s8, s7, 56
	s_sub_i32 s9, s27, s8
	s_sext_i32_i16 s10, s9
	s_lshl_b32 s8, s10, 6
	s_and_b32 s9, s9, 0xffff
	s_cmp_lt_u32 s9, 48
	s_cselect_b32 s9, 4, 12
	s_cmp_gt_i32 s10, 23
	s_cselect_b32 s9, s9, 0
	s_or_b32 s10, s9, s8
	s_mul_i32 s11, s6, 0xe0c000
	s_mul_hi_i32 s9, s6, 0xe0c000
	s_add_u32 s11, s90, s11
	s_addc_u32 s9, s91, s9
	s_lshl_b32 s12, s7, 6
	s_ashr_i32 s13, s12, 31
	s_mul_i32 s7, s7, 0xe0c00
	s_mul_hi_i32 s14, s12, 0x3830
	s_add_u32 s7, s11, s7
	s_addc_u32 s9, s9, s14
	s_ashr_i32 s11, s10, 31
	s_lshl_b64 s[10:11], s[10:11], 2
	s_add_u32 s10, s7, s10
	s_addc_u32 s11, s9, s11
	s_mul_hi_i32 s7, s6, 0x700000
	s_mul_i32 s6, s6, 0x700000
	s_add_u32 s14, s25, s6
	s_addc_u32 s15, s26, s7
	s_ashr_i32 s9, s8, 31
	s_lshl_b64 s[6:7], s[8:9], 11
	s_add_u32 s8, s14, s6
	s_addc_u32 s9, s15, s7
	s_lshl_b64 s[6:7], s[12:13], 1
	s_add_u32 s8, s8, s6
	s_addc_u32 s9, s9, s7
	s_mov_b64 s[12:13], 0x400
	s_mov_b64 s[14:15], 0xe0c
; __device__ __forceinline__ int my_gdim() { int t = (int)gridDim.x; asm volatile("" : "+s"(t)); return t; }
; __device__ void phase_prologue(const Params& p, unsigned char* lds) {
;     ...
;         if (it < N_T) { d = tdesc(it); v0 = *(const f32x4*)(d.src + (size_t)kk0 * d.ldsrc + n4); v1 = *(const f32x4*)(d.src + (size_t)(kk0 + 32) * d.ldsrc + n4); }
;         while (it < N_T) {
;             const int itn = it + my_gdim(); TD dn{nullptr, nullptr, 0, 0}; f32x4 w0 = (f32x4){0.f, 0.f, 0.f, 0.f}, w1 = w0;
;             if (itn < N_T) { dn = tdesc(itn); w0 = *(const f32x4*)(dn.src + (size_t)kk0 * dn.ldsrc + n4); w1 = *(const f32x4*)(dn.src + (size_t)(kk0 + 32) * dn.ldsrc + n4); }
;             tile[kk0 * 65 + n4] = v0[0]; tile[kk0 * 65 + n4 + 1] = v0[1]; tile[kk0 * 65 + n4 + 2] = v0[2]; tile[kk0 * 65 + n4 + 3] = v0[3];
;             tile[(kk0 + 32) * 65 + n4] = v1[0]; tile[(kk0 + 32) * 65 + n4 + 1] = v1[1]; tile[(kk0 + 32) * 65 + n4 + 2] = v1[2]; tile[(kk0 + 32) * 65 + n4 + 3] = v1[3];
;             __syncthreads();
.Lp0_havea:
	s_mov_b32 m0, s30
	s_nop 0
	v_writelane_b32 v108, s10, m0
	s_add_i32 m0, m0, 1
	s_nop 0
	v_writelane_b32 v108, s11, m0
	s_add_i32 m0, m0, 1
	s_nop 0
	v_writelane_b32 v108, s14, m0
	s_add_i32 m0, m0, 1
	s_nop 0
	v_writelane_b32 v108, s8, m0
	s_add_i32 m0, m0, 1
	s_nop 0
	v_writelane_b32 v108, s9, m0
	s_add_i32 m0, m0, 1
	s_nop 0
	v_writelane_b32 v108, s12, m0
	s_add_i32 s28, s28, s29
	s_add_i32 s30, s30, 6
	s_cmp_lt_u32 s30, 54
	s_cbranch_scc1 .Lp0_para
	v_readlane_b32 s10, v108, 0
	v_readlane_b32 s11, v108, 1
	v_readlane_b32 s14, v108, 2
	s_nop 1
	v_mul_lo_u32 v2, v20, s14
	v_add_lshl_u32 v2, v2, v22, 2
	s_lshl_b32 s15, s14, 7
	v_add_u32_e32 v3, s15, v2
	s_nop 1
	global_load_dwordx4 v[36:39], v2, s[10:11]
	global_load_dwordx4 v[40:43], v3, s[10:11]
	v_readlane_b32 s10, v108, 6
	v_readlane_b32 s11, v108, 7
	v_readlane_b32 s14, v108, 8
	s_nop 1
	v_mul_lo_u32 v2, v20, s14
	v_add_lshl_u32 v2, v2, v22, 2
	s_lshl_b32 s15, s14, 7
	v_add_u32_e32 v3, s15, v2
	s_nop 1
	global_load_dwordx4 v[44:47], v2, s[10:11]
	global_load_dwordx4 v[48:51], v3, s[10:11]
	v_readlane_b32 s10, v108, 12
	v_readlane_b32 s11, v108, 13
	v_readlane_b32 s14, v108, 14
	s_nop 1
	v_mul_lo_u32 v2, v20, s14
	v_add_lshl_u32 v2, v2, v22, 2
	s_lshl_b32 s15, s14, 7
	v_add_u32_e32 v3, s15, v2
	s_nop 1
	global_load_dwordx4 v[52:55], v2, s[10:11]
	global_load_dwordx4 v[56:59], v3, s[10:11]
	v_readlane_b32 s10, v108, 18
	v_readlane_b32 s11, v108, 19
	v_readlane_b32 s14, v108, 20
	s_nop 1
	v_mul_lo_u32 v2, v20, s14
	v_add_lshl_u32 v2, v2, v22, 2
	s_lshl_b32 s15, s14, 7
	v_add_u32_e32 v3, s15, v2
	s_nop 1
	global_load_dwordx4 v[60:63], v2, s[10:11]
	global_load_dwordx4 v[64:67], v3, s[10:11]
	v_readlane_b32 s10, v108, 24
	v_readlane_b32 s11, v108, 25
	v_readlane_b32 s14, v108, 26
	s_nop 1
	v_mul_lo_u32 v2, v20, s14
	v_add_lshl_u32 v2, v2, v22, 2
	s_lshl_b32 s15, s14, 7
	v_add_u32_e32 v3, s15, v2
	s_nop 1
	global_load_dwordx4 v[68:71], v2, s[10:11]
	global_load_dwordx4 v[72:75], v3, s[10:11]
	v_readlane_b32 s10, v108, 30
	v_readlane_b32 s11, v108, 31
	v_readlane_b32 s14, v108, 32
	s_nop 1
	v_mul_lo_u32 v2, v20, s14
	v_add_lshl_u32 v2, v2, v22, 2
	s_lshl_b32 s15, s14, 7
	v_add_u32_e32 v3, s15, v2
	s_nop 1
	global_load_dwordx4 v[76:79], v2, s[10:11]
	global_load_dwordx4 v[80:83], v3, s[10:11]
	v_readlane_b32 s10, v108, 36
	v_readlane_b32 s11, v108, 37
	v_readlane_b32 s14, v108, 38
	s_nop 1
	v_mul_lo_u32 v2, v20, s14
	v_add_lshl_u32 v2, v2, v22, 2
	s_lshl_b32 s15, s14, 7
	v_add_u32_e32 v3, s15, v2
	s_nop 1
	global_load_dwordx4 v[84:87], v2, s[10:11]
	global_load_dwordx4 v[88:91], v3, s[10:11]
	v_readlane_b32 s10, v108, 42
	v_readlane_b32 s11, v108, 43
	v_readlane_b32 s14, v108, 44
	s_nop 1
	v_mul_lo_u32 v2, v20, s14
	v_add_lshl_u32 v2, v2, v22, 2
	s_lshl_b32 s15, s14, 7
	v_add_u32_e32 v3, s15, v2
	s_nop 1
	global_load_dwordx4 v[92:95], v2, s[10:11]
	global_load_dwordx4 v[96:99], v3, s[10:11]
	v_readlane_b32 s10, v108, 48
	v_readlane_b32 s11, v108, 49
	v_readlane_b32 s14, v108, 50
	s_nop 1
	v_mul_lo_u32 v2, v20, s14
	v_add_lshl_u32 v2, v2, v22, 2
	s_lshl_b32 s15, s14, 7
	v_add_u32_e32 v3, s15, v2
	s_nop 1
	global_load_dwordx4 v[100:103], v2, s[10:11]
	global_load_dwordx4 v[104:107], v3, s[10:11]
	s_waitcnt vmcnt(0)
.Lp0_loop:
	s_waitcnt vmcnt(25)
	v_add_u32_e32 v4, 0x0, v110
	ds_write2_b32 v4, v36, v37 offset1:1
	ds_write2_b32 v4, v38, v39 offset0:2 offset1:3
	v_add_u32_e32 v5, 0x2080, v110
	ds_write2_b32 v5, v40, v41 offset1:1
	ds_write2_b32 v5, v42, v43 offset0:2 offset1:3
	s_waitcnt vmcnt(23)
	v_add_u32_e32 v4, 0x4100, v110
	ds_write2_b32 v4, v44, v45 offset1:1
	ds_write2_b32 v4, v46, v47 offset0:2 offset1:3
	v_add_u32_e32 v5, 0x6180, v110
	ds_write2_b32 v5, v48, v49 offset1:1
	ds_write2_b32 v5, v50, v51 offset0:2 offset1:3
	s_waitcnt vmcnt(21)
	v_add_u32_e32 v4, 0x8200, v110
	ds_write2_b32 v4, v52, v53 offset1:1
	ds_write2_b32 v4, v54, v55 offset0:2 offset1:3
	v_add_u32_e32 v5, 0xa280, v110
	ds_write2_b32 v5, v56, v57 offset1:1
	ds_write2_b32 v5, v58, v59 offset0:2 offset1:3
	s_waitcnt vmcnt(19)
	v_add_u32_e32 v4, 0xc300, v110
	ds_write2_b32 v4, v60, v61 offset1:1
	ds_write2_b32 v4, v62, v63 offset0:2 offset1:3
	v_add_u32_e32 v5, 0xe380, v110
	ds_write2_b32 v5, v64, v65 offset1:1
	ds_write2_b32 v5, v66, v67 offset0:2 offset1:3
	s_waitcnt vmcnt(17)
	v_add_u32_e32 v4, 0x10400, v110
	ds_write2_b32 v4, v68, v69 offset1:1
	ds_write2_b32 v4, v70, v71 offset0:2 offset1:3
	v_add_u32_e32 v5, 0x12480, v110
	ds_write2_b32 v5, v72, v73 offset1:1
	ds_write2_b32 v5, v74, v75 offset0:2 offset1:3
	s_waitcnt vmcnt(15)
	v_add_u32_e32 v4, 0x14500, v110
	ds_write2_b32 v4, v76, v77 offset1:1
	ds_write2_b32 v4, v78, v79 offset0:2 offset1:3
	v_add_u32_e32 v5, 0x16580, v110
	ds_write2_b32 v5, v80, v81 offset1:1
	ds_write2_b32 v5, v82, v83 offset0:2 offset1:3
	s_waitcnt vmcnt(13)
	v_add_u32_e32 v4, 0x18600, v110
	ds_write2_b32 v4, v84, v85 offset1:1
	ds_write2_b32 v4, v86, v87 offset0:2 offset1:3
	v_add_u32_e32 v5, 0x1a680, v110
	ds_write2_b32 v5, v88, v89 offset1:1
	ds_write2_b32 v5, v90, v91 offset0:2 offset1:3
	s_waitcnt vmcnt(11)
	v_add_u32_e32 v4, 0x1c700, v110
	ds_write2_b32 v4, v92, v93 offset1:1
	ds_write2_b32 v4, v94, v95 offset0:2 offset1:3
	v_add_u32_e32 v5, 0x1e780, v110
	ds_write2_b32 v5, v96, v97 offset1:1
	ds_write2_b32 v5, v98, v99 offset0:2 offset1:3
	s_waitcnt vmcnt(9)
	v_add_u32_e32 v4, 0x20800, v110
	ds_write2_b32 v4, v100, v101 offset1:1
	ds_write2_b32 v4, v102, v103 offset0:2 offset1:3
	v_add_u32_e32 v5, 0x22880, v110
	ds_write2_b32 v5, v104, v105 offset1:1
	ds_write2_b32 v5, v106, v107 offset0:2 offset1:3
	s_waitcnt lgkmcnt(0)
	v_mov_b32_e32 v109, v108
	s_add_i32 s31, s31, s35
	s_cmp_gt_i32 s31, 0x197f
	s_cbranch_scc1 .Lp0_nonext
	s_mov_b32 s28, s31
	s_mov_b32 s30, 0

; __device__ __forceinline__ int my_gdim() { int t = (int)gridDim.x; asm volatile("" : "+s"(t)); return t; }
; __device__ void phase_prologue(const Params& p, unsigned char* lds) {
;     ...
;             const int itn = it + my_gdim(); TD dn{nullptr, nullptr, 0, 0}; f32x4 w0 = (f32x4){0.f, 0.f, 0.f, 0.f}, w1 = w0;
;             if (itn < N_T) { dn = tdesc(itn); w0 = *(const f32x4*)(dn.src + (size_t)kk0 * dn.ldsrc + n4); w1 = *(const f32x4*)(dn.src + (size_t)(kk0 + 32) * dn.ldsrc + n4); }
.Lp0_haveb:
	s_mov_b32 m0, s30
	s_nop 0
	v_writelane_b32 v108, s10, m0
	s_add_i32 m0, m0, 1
	s_nop 0
	v_writelane_b32 v108, s11, m0
	s_add_i32 m0, m0, 1
	s_nop 0
	v_writelane_b32 v108, s14, m0
	s_add_i32 m0, m0, 1
	s_nop 0
	v_writelane_b32 v108, s8, m0
	s_add_i32 m0, m0, 1
	s_nop 0
	v_writelane_b32 v108, s9, m0
	s_add_i32 m0, m0, 1
	s_nop 0
	v_writelane_b32 v108, s12, m0
	s_add_i32 s28, s28, s29
	s_add_i32 s30, s30, 6
	s_cmp_lt_u32 s30, 54
	s_cbranch_scc1 .Lp0_parb
	v_readlane_b32 s10, v108, 0
	v_readlane_b32 s11, v108, 1
	v_readlane_b32 s14, v108, 2
	s_nop 1
	v_mul_lo_u32 v2, v20, s14
	v_add_lshl_u32 v2, v2, v22, 2
	s_lshl_b32 s15, s14, 7
	v_add_u32_e32 v3, s15, v2
	s_nop 1
	global_load_dwordx4 v[36:39], v2, s[10:11]
	global_load_dwordx4 v[40:43], v3, s[10:11]
	v_readlane_b32 s10, v108, 6
	v_readlane_b32 s11, v108, 7
	v_readlane_b32 s14, v108, 8
	s_nop 1
	v_mul_lo_u32 v2, v20, s14
	v_add_lshl_u32 v2, v2, v22, 2
	s_lshl_b32 s15, s14, 7
	v_add_u32_e32 v3, s15, v2
	s_nop 1
	global_load_dwordx4 v[44:47], v2, s[10:11]
	global_load_dwordx4 v[48:51], v3, s[10:11]
	v_readlane_b32 s10, v108, 12
	v_readlane_b32 s11, v108, 13
	v_readlane_b32 s14, v108, 14
	s_nop 1
	v_mul_lo_u32 v2, v20, s14
	v_add_lshl_u32 v2, v2, v22, 2
	s_lshl_b32 s15, s14, 7
	v_add_u32_e32 v3, s15, v2
	s_nop 1
	global_load_dwordx4 v[52:55], v2, s[10:11]
	global_load_dwordx4 v[56:59], v3, s[10:11]
	v_readlane_b32 s10, v108, 18
	v_readlane_b32 s11, v108, 19
	v_readlane_b32 s14, v108, 20
	s_nop 1
	v_mul_lo_u32 v2, v20, s14
	v_add_lshl_u32 v2, v2, v22, 2
	s_lshl_b32 s15, s14, 7
	v_add_u32_e32 v3, s15, v2
	s_nop 1
	global_load_dwordx4 v[60:63], v2, s[10:11]
	global_load_dwordx4 v[64:67], v3, s[10:11]
	v_readlane_b32 s10, v108, 24
	v_readlane_b32 s11, v108, 25
	v_readlane_b32 s14, v108, 26
	s_nop 1
	v_mul_lo_u32 v2, v20, s14
	v_add_lshl_u32 v2, v2, v22, 2
	s_lshl_b32 s15, s14, 7
	v_add_u32_e32 v3, s15, v2
	s_nop 1
	global_load_dwordx4 v[68:71], v2, s[10:11]
	global_load_dwordx4 v[72:75], v3, s[10:11]
	v_readlane_b32 s10, v108, 30
	v_readlane_b32 s11, v108, 31
	v_readlane_b32 s14, v108, 32
	s_nop 1
	v_mul_lo_u32 v2, v20, s14
	v_add_lshl_u32 v2, v2, v22, 2
	s_lshl_b32 s15, s14, 7
	v_add_u32_e32 v3, s15, v2
	s_nop 1
	global_load_dwordx4 v[76:79], v2, s[10:11]
	global_load_dwordx4 v[80:83], v3, s[10:11]
	v_readlane_b32 s10, v108, 36
	v_readlane_b32 s11, v108, 37
	v_readlane_b32 s14, v108, 38
	s_nop 1
	v_mul_lo_u32 v2, v20, s14
	v_add_lshl_u32 v2, v2, v22, 2
	s_lshl_b32 s15, s14, 7
	v_add_u32_e32 v3, s15, v2
	s_nop 1
	global_load_dwordx4 v[84:87], v2, s[10:11]
	global_load_dwordx4 v[88:91], v3, s[10:11]
	v_readlane_b32 s10, v108, 42
	v_readlane_b32 s11, v108, 43
	v_readlane_b32 s14, v108, 44
	s_nop 1
	v_mul_lo_u32 v2, v20, s14
	v_add_lshl_u32 v2, v2, v22, 2
	s_lshl_b32 s15, s14, 7
	v_add_u32_e32 v3, s15, v2
	s_nop 1
	global_load_dwordx4 v[92:95], v2, s[10:11]
	global_load_dwordx4 v[96:99], v3, s[10:11]
	v_readlane_b32 s10, v108, 48
	v_readlane_b32 s11, v108, 49
	v_readlane_b32 s14, v108, 50
	s_nop 1
	v_mul_lo_u32 v2, v20, s14
	v_add_lshl_u32 v2, v2, v22, 2
	s_lshl_b32 s15, s14, 7
	v_add_u32_e32 v3, s15, v2
	s_nop 1
	global_load_dwordx4 v[100:103], v2, s[10:11]
	global_load_dwordx4 v[104:107], v3, s[10:11]
; __device__ __forceinline__ unsigned pack2(float lo, float hi) { return pg8::cvt_pk_bf16(lo, hi); }
; __device__ void phase_prologue(const Params& p, unsigned char* lds) {
;     ...
;             __syncthreads();
;             u32x4 w;
;             w.x = pack2(tile[(k8 + 0) * 65 + nn], tile[(k8 + 1) * 65 + nn]); w.y = pack2(tile[(k8 + 2) * 65 + nn], tile[(k8 + 3) * 65 + nn]);
;             w.z = pack2(tile[(k8 + 4) * 65 + nn], tile[(k8 + 5) * 65 + nn]); w.w = pack2(tile[(k8 + 6) * 65 + nn], tile[(k8 + 7) * 65 + nn]);
;             *(u32x4*)(d.dst + (size_t)nn * d.ldd + k8) = w;
;             __syncthreads();
;             it = itn; d = dn; v0 = w0; v1 = w1;
.Lp0_nonext:
	s_barrier
	v_add_u32_e32 v32, 0x0, v111
	v_add_u32_e32 v33, 0x200, v111
	v_add_u32_e32 v34, 0x400, v111
	ds_read_b32 v8, v32
	ds_read2_b32 v[2:3], v32 offset0:65 offset1:130
	ds_read2_b32 v[4:5], v33 offset0:67 offset1:132
	ds_read2_b32 v[6:7], v34 offset0:69 offset1:134
	ds_read_b32 v9, v32 offset:1820
	v_add_u32_e32 v32, 0x4100, v111
	v_add_u32_e32 v33, 0x4300, v111
	v_add_u32_e32 v34, 0x4500, v111
	ds_read_b32 v16, v32
	ds_read2_b32 v[10:11], v32 offset0:65 offset1:130
	ds_read2_b32 v[12:13], v33 offset0:67 offset1:132
	ds_read2_b32 v[14:15], v34 offset0:69 offset1:134
	ds_read_b32 v17, v32 offset:1820
	v_add_u32_e32 v32, 0x8200, v111
	v_add_u32_e32 v33, 0x8400, v111
	v_add_u32_e32 v34, 0x8600, v111
	ds_read_b32 v30, v32
	ds_read2_b32 v[24:25], v32 offset0:65 offset1:130
	ds_read2_b32 v[26:27], v33 offset0:67 offset1:132
	ds_read2_b32 v[28:29], v34 offset0:69 offset1:134
	ds_read_b32 v31, v32 offset:1820
	v_readlane_b32 s8, v109, 3
	v_readlane_b32 s9, v109, 4
	v_readlane_b32 s12, v109, 5
	s_nop 1
	v_mul_lo_u32 v35, v112, s12
	v_lshl_add_u32 v35, v35, 1, v113
	s_waitcnt lgkmcnt(10)
	v_cvt_pk_bf16_f32 v2, v8, v2
	v_cvt_pk_bf16_f32 v3, v3, v4
	v_cvt_pk_bf16_f32 v4, v5, v6
	v_cvt_pk_bf16_f32 v5, v7, v9
	s_nop 0
	global_store_dwordx4 v35, v[2:5], s[8:9]
	v_readlane_b32 s8, v109, 9
	v_readlane_b32 s9, v109, 10
	v_readlane_b32 s12, v109, 11
	s_nop 1
	v_mul_lo_u32 v35, v112, s12
	v_lshl_add_u32 v35, v35, 1, v113
	s_waitcnt lgkmcnt(5)
	v_cvt_pk_bf16_f32 v10, v16, v10
	v_cvt_pk_bf16_f32 v11, v11, v12
	v_cvt_pk_bf16_f32 v12, v13, v14
	v_cvt_pk_bf16_f32 v13, v15, v17
	s_nop 0
	global_store_dwordx4 v35, v[10:13], s[8:9]
	v_readlane_b32 s8, v109, 15
	v_readlane_b32 s9, v109, 16
	v_readlane_b32 s12, v109, 17
	s_nop 1
	v_mul_lo_u32 v35, v112, s12
	v_lshl_add_u32 v35, v35, 1, v113
	s_waitcnt lgkmcnt(0)
	v_cvt_pk_bf16_f32 v24, v30, v24
	v_cvt_pk_bf16_f32 v25, v25, v26
	v_cvt_pk_bf16_f32 v26, v27, v28
	v_cvt_pk_bf16_f32 v27, v29, v31
	s_nop 0
	global_store_dwordx4 v35, v[24:27], s[8:9]
	v_add_u32_e32 v32, 0xc300, v111
	v_add_u32_e32 v33, 0xc500, v111
	v_add_u32_e32 v34, 0xc700, v111
	ds_read_b32 v8, v32
	ds_read2_b32 v[2:3], v32 offset0:65 offset1:130
	ds_read2_b32 v[4:5], v33 offset0:67 offset1:132
	ds_read2_b32 v[6:7], v34 offset0:69 offset1:134
	ds_read_b32 v9, v32 offset:1820
	v_add_u32_e32 v32, 0x10400, v111
	v_add_u32_e32 v33, 0x10600, v111
	v_add_u32_e32 v34, 0x10800, v111
	ds_read_b32 v16, v32
	ds_read2_b32 v[10:11], v32 offset0:65 offset1:130
	ds_read2_b32 v[12:13], v33 offset0:67 offset1:132
	ds_read2_b32 v[14:15], v34 offset0:69 offset1:134
	ds_read_b32 v17, v32 offset:1820
	v_add_u32_e32 v32, 0x14500, v111
	v_add_u32_e32 v33, 0x14700, v111
	v_add_u32_e32 v34, 0x14900, v111
	ds_read_b32 v30, v32
	ds_read2_b32 v[24:25], v32 offset0:65 offset1:130
	ds_read2_b32 v[26:27], v33 offset0:67 offset1:132
	ds_read2_b32 v[28:29], v34 offset0:69 offset1:134
	ds_read_b32 v31, v32 offset:1820
	v_readlane_b32 s8, v109, 21
	v_readlane_b32 s9, v109, 22
	v_readlane_b32 s12, v109, 23
	s_nop 1
	v_mul_lo_u32 v35, v112, s12
	v_lshl_add_u32 v35, v35, 1, v113
	s_waitcnt lgkmcnt(10)
	v_cvt_pk_bf16_f32 v2, v8, v2
	v_cvt_pk_bf16_f32 v3, v3, v4
	v_cvt_pk_bf16_f32 v4, v5, v6
	v_cvt_pk_bf16_f32 v5, v7, v9
	s_nop 0
	global_store_dwordx4 v35, v[2:5], s[8:9]
	v_readlane_b32 s8, v109, 27
	v_readlane_b32 s9, v109, 28
	v_readlane_b32 s12, v109, 29
	s_nop 1
	v_mul_lo_u32 v35, v112, s12
	v_lshl_add_u32 v35, v35, 1, v113
	s_waitcnt lgkmcnt(5)
	v_cvt_pk_bf16_f32 v10, v16, v10
	v_cvt_pk_bf16_f32 v11, v11, v12
	v_cvt_pk_bf16_f32 v12, v13, v14
	v_cvt_pk_bf16_f32 v13, v15, v17
	s_nop 0
	global_store_dwordx4 v35, v[10:13], s[8:9]
	v_readlane_b32 s8, v109, 33
	v_readlane_b32 s9, v109, 34
	v_readlane_b32 s12, v109, 35
	s_nop 1
	v_mul_lo_u32 v35, v112, s12
	v_lshl_add_u32 v35, v35, 1, v113
	s_waitcnt lgkmcnt(0)
	v_cvt_pk_bf16_f32 v24, v30, v24
	v_cvt_pk_bf16_f32 v25, v25, v26
	v_cvt_pk_bf16_f32 v26, v27, v28
	v_cvt_pk_bf16_f32 v27, v29, v31
	s_nop 0
	global_store_dwordx4 v35, v[24:27], s[8:9]
	v_add_u32_e32 v32, 0x18600, v111
	v_add_u32_e32 v33, 0x18800, v111
	v_add_u32_e32 v34, 0x18a00, v111
	ds_read_b32 v8, v32
	ds_read2_b32 v[2:3], v32 offset0:65 offset1:130
	ds_read2_b32 v[4:5], v33 offset0:67 offset1:132
	ds_read2_b32 v[6:7], v34 offset0:69 offset1:134
	ds_read_b32 v9, v32 offset:1820
	v_add_u32_e32 v32, 0x1c700, v111
	v_add_u32_e32 v33, 0x1c900, v111
	v_add_u32_e32 v34, 0x1cb00, v111
	ds_read_b32 v16, v32
	ds_read2_b32 v[10:11], v32 offset0:65 offset1:130
	ds_read2_b32 v[12:13], v33 offset0:67 offset1:132
	ds_read2_b32 v[14:15], v34 offset0:69 offset1:134
	ds_read_b32 v17, v32 offset:1820
	v_add_u32_e32 v32, 0x20800, v111
	v_add_u32_e32 v33, 0x20a00, v111
	v_add_u32_e32 v34, 0x20c00, v111
	ds_read_b32 v30, v32
	ds_read2_b32 v[24:25], v32 offset0:65 offset1:130
	ds_read2_b32 v[26:27], v33 offset0:67 offset1:132
	ds_read2_b32 v[28:29], v34 offset0:69 offset1:134
	ds_read_b32 v31, v32 offset:1820
	v_readlane_b32 s8, v109, 39
	v_readlane_b32 s9, v109, 40
	v_readlane_b32 s12, v109, 41
	s_nop 1
	v_mul_lo_u32 v35, v112, s12
	v_lshl_add_u32 v35, v35, 1, v113
	s_waitcnt lgkmcnt(10)
	v_cvt_pk_bf16_f32 v2, v8, v2
	v_cvt_pk_bf16_f32 v3, v3, v4
	v_cvt_pk_bf16_f32 v4, v5, v6
	v_cvt_pk_bf16_f32 v5, v7, v9
	s_nop 0
	global_store_dwordx4 v35, v[2:5], s[8:9]
	v_readlane_b32 s8, v109, 45
	v_readlane_b32 s9, v109, 46
	v_readlane_b32 s12, v109, 47
	s_nop 1
	v_mul_lo_u32 v35, v112, s12
	v_lshl_add_u32 v35, v35, 1, v113
	s_waitcnt lgkmcnt(5)
	v_cvt_pk_bf16_f32 v10, v16, v10
	v_cvt_pk_bf16_f32 v11, v11, v12
	v_cvt_pk_bf16_f32 v12, v13, v14
	v_cvt_pk_bf16_f32 v13, v15, v17
	s_nop 0
	global_store_dwordx4 v35, v[10:13], s[8:9]
	v_readlane_b32 s8, v109, 51
	v_readlane_b32 s9, v109, 52
	v_readlane_b32 s12, v109, 53
	s_nop 1
	v_mul_lo_u32 v35, v112, s12
	v_lshl_add_u32 v35, v35, 1, v113
	s_waitcnt lgkmcnt(0)
	v_cvt_pk_bf16_f32 v24, v30, v24
	v_cvt_pk_bf16_f32 v25, v25, v26
	v_cvt_pk_bf16_f32 v26, v27, v28
	v_cvt_pk_bf16_f32 v27, v29, v31
	s_nop 0
	global_store_dwordx4 v35, v[24:27], s[8:9]
	s_waitcnt lgkmcnt(0)
	s_barrier
	s_cmp_le_i32 s31, 0x197f
	s_cbranch_scc1 .Lp0_loop
	s_waitcnt vmcnt(0)
	s_movk_i32 s84, 0x77

; __device__ __forceinline__ int my_bid() { int t = (int)blockIdx.x; asm volatile("" : "+s"(t)); return t; }
; __device__ __forceinline__ int my_gdim() { int t = (int)gridDim.x; asm volatile("" : "+s"(t)); return t; }
; __device__ void phase_prologue(const Params& p, unsigned char* lds) {
;     ...
;     for (int it = my_bid(); it < N_ALL; it += my_gdim()) {
;         if (it < N_T) {
;             continue;
;         } else if (it < N_T + N_MOD) {
;     ...
;             const int r = it - N_T - N_MOD, l = r / 12, j = r % 12; const int sc = j < 4 ? 1536 + j : (j < 8 ? 3076 + (j - 4) : 3080 + (j - 8));
;             float* dst = (float*)(p.ws + WS_WSC) + ((size_t)l * 12 + j) * DM; const float* src = p.in[I_WIN] + (size_t)l * DM * DIN + sc;
;             for (int k = tid; k < DM; k += NTHR) dst[k] = src[(size_t)k * DIN];
.LBB0_738:
	s_load_dword s2, s[80:81], 0x0
	s_waitcnt lgkmcnt(0)
	s_add_i32 s14, s2, s14
	s_cmpk_gt_i32 s14, 0x1a57
	s_cbranch_scc1 .LBB0_767
	s_branch .Lrp_1
	s_nop 0
	s_nop 0
	s_nop 0
	s_nop 0
	s_nop 0
	s_nop 0
	s_nop 0
	s_nop 0
	s_nop 0
	s_nop 0
	s_nop 0
	s_nop 0
	s_nop 0
	s_nop 0
	s_nop 0
	s_nop 0
	s_nop 0
	s_nop 0
	s_nop 0
	s_nop 0
	s_nop 0
	s_nop 0
	s_nop 0
	s_nop 0
	s_nop 0
	s_nop 0
	s_nop 0
	s_nop 0
	s_nop 0
	s_nop 0
	s_nop 0
	s_nop 0
	s_nop 0
	s_nop 0
	s_nop 0
	s_nop 0
	s_nop 0
	s_nop 0
	s_nop 0
	s_nop 0
	s_nop 0
	s_nop 0
	s_nop 0
	s_nop 0
	s_nop 0
	s_nop 0
	s_nop 0
	s_nop 0
	s_nop 0
	s_nop 0
	s_nop 0
	s_nop 0
	s_nop 0
	s_nop 0
	s_nop 0
	s_nop 0
	s_nop 0
	s_nop 0
	s_nop 0
	s_nop 0
	s_nop 0
	s_nop 0
	s_nop 0
	s_nop 0
	s_nop 0
	s_nop 0
	s_nop 0
	s_nop 0
	s_nop 0
	s_nop 0
	s_nop 0
	s_nop 0
	s_nop 0
	s_nop 0
	s_nop 0
	s_nop 0
	s_nop 0
	s_nop 0
	s_nop 0
	s_nop 0
	s_nop 0
	s_nop 0
	s_nop 0
	s_nop 0
	s_nop 0
	s_nop 0
	s_nop 0
	s_nop 0
	s_nop 0
	s_nop 0
	s_nop 0
	s_nop 0
	s_nop 0
	s_nop 0
	s_nop 0
	s_nop 0
	s_nop 0
	s_nop 0
	s_nop 0
	s_nop 0
	s_nop 0
	s_nop 0
	s_nop 0
	s_nop 0
	s_nop 0
	s_nop 0
	s_nop 0
	s_nop 0
	s_nop 0
	s_nop 0
	s_nop 0
	s_nop 0
	s_nop 0
	s_nop 0
	s_nop 0
	s_nop 0
	s_nop 0
	s_nop 0
	s_nop 0
	s_nop 0
	s_nop 0
	s_nop 0
	s_nop 0
	s_nop 0
	s_nop 0
	s_nop 0
	s_nop 0
	s_nop 0
	s_nop 0
	s_nop 0
	s_nop 0
	s_nop 0
	s_nop 0
	s_nop 0
	s_nop 0
	s_nop 0
	s_nop 0
	s_nop 0
	s_nop 0
	s_nop 0
	s_nop 0
	s_nop 0
	s_nop 0
	s_nop 0
	s_nop 0
	s_nop 0
	s_nop 0
	s_nop 0
	s_nop 0
	s_nop 0
	s_nop 0
	s_nop 0
	s_nop 0
	s_nop 0
	s_nop 0
	s_nop 0
	s_nop 0
	s_nop 0
	s_nop 0
	s_nop 0
	s_nop 0
	s_nop 0
	s_nop 0
	s_nop 0
	s_nop 0
	s_nop 0
	s_nop 0
	s_nop 0
	s_nop 0
	s_nop 0
	s_nop 0
	s_nop 0
	s_nop 0
	s_nop 0
	s_nop 0
	s_nop 0
	s_nop 0
	s_nop 0
	s_nop 0
	s_nop 0
	s_nop 0
	s_nop 0
	s_nop 0
	s_nop 0
	s_nop 0
	s_nop 0
	s_nop 0
	s_nop 0
	s_nop 0
	s_nop 0
	s_nop 0
	s_nop 0
	s_nop 0
	s_nop 0
	s_nop 0
	s_nop 0
	s_nop 0
	s_nop 0
	s_nop 0
	s_nop 0
	s_nop 0
	s_nop 0
	s_nop 0
	s_nop 0
	s_nop 0
	s_nop 0
	s_nop 0
	s_nop 0
	s_nop 0
	s_nop 0
	s_nop 0
	s_nop 0
	s_nop 0
	s_nop 0
	s_nop 0
	s_nop 0
	s_nop 0
	s_nop 0
	s_nop 0
	s_nop 0
	s_nop 0
	s_nop 0
	s_nop 0
	s_nop 0
	s_nop 0
	s_nop 0
	s_nop 0
	s_nop 0
	s_nop 0
	s_nop 0
	s_nop 0
	s_nop 0
	s_nop 0
	s_nop 0
	s_nop 0
	s_nop 0
	s_nop 0
	s_nop 0
	s_nop 0
	s_nop 0
	s_nop 0
	s_nop 0
	s_nop 0
	s_nop 0
	s_nop 0
	s_nop 0
	s_nop 0
	s_nop 0
	s_nop 0
	s_nop 0
	s_nop 0
	s_nop 0
	s_nop 0
	s_nop 0
	s_nop 0
	s_nop 0
	s_nop 0
	s_nop 0
	s_nop 0
	s_nop 0
	s_nop 0
	s_nop 0
	s_nop 0
	s_nop 0
	s_nop 0
	s_nop 0
	s_nop 0
	s_nop 0
	s_nop 0
	s_nop 0
	s_nop 0
	s_nop 0
	s_nop 0
	s_nop 0
	s_nop 0
	s_nop 0
	s_nop 0
	s_nop 0
	s_nop 0
	s_nop 0
	s_nop 0
	s_nop 0
	s_nop 0
	s_nop 0
	s_nop 0
	s_nop 0
	s_nop 0
	s_nop 0
	s_nop 0
	s_nop 0
	s_nop 0
	s_nop 0
	s_nop 0
	s_nop 0
	s_nop 0
	s_nop 0
	s_nop 0
	s_nop 0
	s_nop 0
	s_nop 0
	s_nop 0
	s_nop 0
	s_nop 0
	s_nop 0
	s_nop 0
	s_nop 0
	s_nop 0
	s_nop 0
	s_nop 0
	s_nop 0
	s_nop 0
	s_nop 0
	s_nop 0
	s_nop 0
	s_nop 0
	s_nop 0
	s_nop 0
	s_nop 0
	s_nop 0
	s_nop 0
	s_nop 0
	s_nop 0
	s_nop 0
	s_nop 0
	s_nop 0
	s_nop 0
	s_nop 0
	s_nop 0
	s_nop 0
	s_nop 0
	s_nop 0
	s_nop 0
.Lrp_1:
.LBB0_739:
	s_cmpk_lt_i32 s14, 0x1980
	s_cbranch_scc1 .LBB0_738
	s_cmpk_gt_u32 s14, 0x1a3f
	s_mov_b64 s[2:3], -1
	s_cbranch_scc0 .LBB0_745
	s_add_i32 s5, s14, 0xffffe5c0
	s_add_i32 s2, s14, 0xffffe5b4
	s_cmp_lt_u32 s5, 12
	s_cselect_b32 s4, s5, s2
	s_and_saveexec_b64 s[2:3], s[6:7]
	s_cbranch_execz .LBB0_744
	s_cmp_gt_u32 s5, 11
	s_cselect_b64 s[12:13], -1, 0
	s_cmp_lt_u32 s4, 4
	s_movk_i32 s5, 0x600
	s_cselect_b32 s5, s5, 0xc00
	s_and_b64 s[16:17], s[12:13], exec
	s_cselect_b32 s15, 12, 0
	s_add_i32 s84, s15, s4
	s_lshl_b64 s[16:17], s[84:85], 12
	s_and_b64 s[12:13], s[12:13], exec
	s_cselect_b32 s12, 0xe0c000, 0
	s_add_i32 s84, s4, s5
	s_lshl_b64 s[4:5], s[84:85], 2
	s_add_u32 s4, s12, s4
	s_addc_u32 s5, 0, s5
	v_lshl_add_u64 v[2:3], v[28:29], 0, s[16:17]
	s_movk_i32 s84, 0x77
	v_lshl_add_u64 v[4:5], v[30:31], 0, s[4:5]
	s_mov_b64 s[4:5], 0
	v_mov_b32_e32 v6, v60

; __device__ __forceinline__ unsigned xb_ld(unsigned* p)              { return __hip_atomic_load(p, __ATOMIC_RELAXED, __HIP_MEMORY_SCOPE_AGENT); }
; __device__ __forceinline__ unsigned xb_add(unsigned* p, unsigned v) { return __hip_atomic_fetch_add(p, v, __ATOMIC_RELAXED, __HIP_MEMORY_SCOPE_AGENT); }
; #define XB_SPIN(cond, bar) do { unsigned _sp = 0; while (cond) { __builtin_amdgcn_s_sleep(1); \
;     if ((++_sp & 255u) == 0u) { if (xb_ld(&(bar)[XB_TMO])) break; if (_sp > XB_SPIN_CAP) { atomicAdd(&(bar)[XB_TMO], 1u); break; } } } } while (0)
; __device__ __forceinline__ void xcd_barrier(const XcdBarrier& b) {
;     ...
;             else XB_SPIN(xb_ld(&bar[XB_TOPGEN]) == tg, bar);
;             __builtin_amdgcn_fence(__ATOMIC_ACQUIRE, "agent");
;             xb_add(&bar[XB_XGEN(b.x)], 1u);
;             asm volatile("s_waitcnt vmcnt(0)" ::: "memory");
;         } else {
;             XB_SPIN(xb_ld(&bar[XB_XGEN(b.x)]) == gen, bar);
;             __builtin_amdgcn_fence(__ATOMIC_ACQUIRE, "agent");
;             asm volatile("s_waitcnt vmcnt(0)" ::: "memory");
;         }
.LBB0_792:
	s_andn2_b64 s[14:15], s[14:15], exec
	s_and_b64 s[20:21], s[20:21], exec
	s_or_b64 s[14:15], s[14:15], s[20:21]
	s_and_saveexec_b64 s[20:21], s[18:19]
	s_cbranch_execz .LBB0_787
	v_mov_b64_e32 v[4:5], s[6:7]
	global_load_dword v0, v[4:5], off sc1
	s_add_i32 s26, s26, 1
	s_or_b64 s[14:15], s[14:15], exec
	s_waitcnt vmcnt(0) lgkmcnt(0)
	v_cmp_ne_u32_e32 vcc, v0, v3
	s_orn2_b64 s[16:17], vcc, exec
	s_branch .LBB0_787
.LBB0_795:
	s_or_b64 exec, exec, s[10:11]
	s_xor_b64 s[6:7], s[12:13], -1
	s_and_saveexec_b64 s[10:11], s[6:7]
	s_xor_b64 s[10:11], exec, s[10:11]
	s_cbranch_execz .LBB0_797
	v_mov_b64_e32 v[2:3], s[8:9]
	global_atomic_add v[2:3], v214, off
